# v118 + MoBA list entries (written right before the RNN|sparse barrier) stored write-through (sc1)
# speedup vs baseline: 1.0026x; 1.0026x over previous
.LBB0_611:
	v_mbcnt_lo_u32_b32 v0, -1, 0
	v_mbcnt_hi_u32_b32 v0, -1, v0
	s_waitcnt lgkmcnt(0)
	v_cmp_gt_u32_e32 vcc, 32, v0
	s_barrier
	s_and_saveexec_b64 s[6:7], vcc
	s_cbranch_execz .LBB0_619
	s_lshl_b32 s4, s78, 2
	s_ashr_i32 s8, s78, 3
	s_and_b32 s5, s4, 28
	s_mul_hi_i32 s4, s8, 0x7c000
	s_mul_i32 s8, s8, 0x7c000
	s_add_u32 s8, s14, s8
	s_addc_u32 s4, s15, s4
	s_add_u32 s8, s8, 0x1f000000
	s_addc_u32 s9, s4, 0
	s_lshl_b32 s4, s88, 7
	v_add_u32_e32 v1, s64, v0
	s_cmp_lg_u32 s5, 0
	v_lshl_or_b32 v0, v0, 2, s4
	s_mov_b32 s4, 0
	s_cselect_b64 s[10:11], -1, 0
	s_cmp_eq_u32 s5, 0
	v_lshl_add_u32 v2, v1, 2, 0
	s_cbranch_scc1 .LBB0_614
	v_add_u32_e32 v1, 0x22400, v2
	ds_read_b32 v1, v1
	v_add_u32_e32 v3, 0x22c00, v2
	ds_read_b32 v3, v3
	s_lshl_b32 s4, s5, 10
	s_add_i32 s5, 0, 0x1e200
	s_waitcnt lgkmcnt(1)
	v_and_b32_e32 v5, 31, v1
	v_add_u32_e32 v6, 0xffff, v5
	v_mul_u32_u24_e32 v6, v6, v5
	v_lshrrev_b16_e32 v7, 15, v6
	v_add_u16_e32 v6, v6, v7
	v_ashrrev_i16_e32 v6, 1, v6
	v_sub_u16_e32 v6, 0, v6
	v_mul_u32_u24_e32 v4, 31, v5
	v_bfe_i32 v6, v6, 0, 16
	v_lshl_add_u32 v5, v5, 2, s5
	v_add_lshl_u32 v4, v4, v6, 8
	ds_read_b32 v6, v5
	v_ashrrev_i32_e32 v5, 31, v4
	v_mov_b32_e32 v7, 0
	s_waitcnt lgkmcnt(1)
	v_and_b32_e32 v9, 0x3ff, v3
	v_lshl_add_u64 v[4:5], v[4:5], 2, s[8:9]
	s_waitcnt lgkmcnt(0)
	v_lshl_add_u64 v[4:5], v[6:7], 2, v[4:5]
	v_lshlrev_b32_e32 v6, 2, v9
	v_add_u32_e32 v8, s4, v0
	v_lshl_add_u64 v[4:5], v[4:5], 0, v[6:7]
	global_store_dword v[4:5], v8, off sc1
	v_bfe_u32 v4, v1, 8, 5
	v_add_u32_e32 v6, 0xffff, v4
	v_mul_u32_u24_e32 v6, v6, v4
	v_lshrrev_b16_e32 v10, 15, v6
	v_add_u16_e32 v6, v6, v10
	v_mul_u32_u24_e32 v5, 31, v4
	v_ashrrev_i16_e32 v6, 1, v6
	v_lshl_add_u32 v4, v4, 2, s5
	v_sub_u16_e32 v10, 0, v6
	ds_read_b32 v6, v4
	v_bfe_i32 v4, v10, 0, 16
	v_add_lshl_u32 v4, v5, v4, 8
	v_ashrrev_i32_e32 v5, 31, v4
	v_lshl_add_u64 v[4:5], v[4:5], 2, s[8:9]
	s_waitcnt lgkmcnt(0)
	v_lshl_add_u64 v[4:5], v[6:7], 2, v[4:5]
	v_lshrrev_b32_e32 v6, 8, v3
	v_and_b32_e32 v6, 0xffc, v6
	v_or_b32_e32 v9, 1, v8
	v_lshl_add_u64 v[4:5], v[4:5], 0, v[6:7]
	v_bfe_u32 v1, v1, 16, 5
	global_store_dword v[4:5], v9, off sc1
	v_add_u32_e32 v5, 0xffff, v1
	v_mul_u32_u24_e32 v5, v5, v1
	v_lshrrev_b16_e32 v6, 15, v5
	v_add_u16_e32 v5, v5, v6
	v_mul_u32_u24_e32 v4, 31, v1
	v_ashrrev_i16_e32 v5, 1, v5
	v_lshl_add_u32 v1, v1, 2, s5
	v_sub_u16_e32 v5, 0, v5
	ds_read_b32 v6, v1
	v_bfe_i32 v1, v5, 0, 16
	v_add_lshl_u32 v4, v4, v1, 8
	v_ashrrev_i32_e32 v5, 31, v4
	v_lshl_add_u64 v[4:5], v[4:5], 2, s[8:9]
	v_lshrrev_b32_e32 v1, 18, v3
	s_waitcnt lgkmcnt(0)
	v_lshl_add_u64 v[4:5], v[6:7], 2, v[4:5]
	v_and_b32_e32 v6, 0xffc, v1
	v_or_b32_e32 v8, 2, v8
	v_lshl_add_u64 v[4:5], v[4:5], 0, v[6:7]
	global_store_dword v[4:5], v8, off sc1
.LBB0_614:
	v_add_u32_e32 v1, 0x23400, v2
	ds_read_b32 v5, v1
	v_add_u32_e32 v3, s4, v0
	v_add_u32_e32 v1, 0x23c00, v2
	ds_read_b32 v4, v1
	v_add_u32_e32 v6, 0x400, v3
	s_waitcnt lgkmcnt(1)
	v_and_b32_e32 v0, 31, v5
	v_add_u32_e32 v7, 0xffff, v0
	v_mul_u32_u24_e32 v7, v7, v0
	v_lshrrev_b16_e32 v8, 15, v7
	v_mul_u32_u24_e32 v1, 31, v0
	v_add_u16_e32 v7, v7, v8
	v_lshl_add_u32 v0, v0, 2, 0
	v_ashrrev_i16_e32 v7, 1, v7
	v_add_u32_e32 v0, 0x1e280, v0
	v_sub_u16_e32 v7, 0, v7
	ds_read_b32 v0, v0
	v_bfe_i32 v7, v7, 0, 16
	v_add_lshl_u32 v8, v1, v7, 8
	v_ashrrev_i32_e32 v9, 31, v8
	v_mov_b32_e32 v1, 0
	s_waitcnt lgkmcnt(1)
	v_and_b32_e32 v7, 0x3ff, v4
	v_lshl_add_u64 v[8:9], v[8:9], 2, s[8:9]
	s_waitcnt lgkmcnt(0)
	v_lshl_add_u64 v[8:9], v[0:1], 2, v[8:9]
	v_lshlrev_b32_e32 v0, 2, v7
	v_lshl_add_u64 v[8:9], v[8:9], 0, v[0:1]
	v_cndmask_b32_e64 v0, 0, 1, s[10:11]
	v_cmp_ne_u32_e64 s[4:5], 1, v0
	s_andn2_b64 vcc, exec, s[10:11]
	global_store_dword v[8:9], v6, off sc1
	s_cbranch_vccnz .LBB0_616
	v_bfe_u32 v0, v5, 8, 5
	v_add_u32_e32 v9, 0xffff, v0
	v_mul_u32_u24_e32 v9, v9, v0
	v_lshrrev_b16_e32 v10, 15, v9
	v_add_u16_e32 v9, v9, v10
	s_add_i32 s10, 0, 0x1e280
	v_mul_u32_u24_e32 v8, 31, v0
	v_ashrrev_i16_e32 v9, 1, v9
	v_lshl_add_u32 v0, v0, 2, s10
	v_sub_u16_e32 v9, 0, v9
	ds_read_b32 v0, v0
	v_bfe_i32 v9, v9, 0, 16
	v_add_lshl_u32 v8, v8, v9, 8
	v_ashrrev_i32_e32 v9, 31, v8
	v_lshl_add_u64 v[8:9], v[8:9], 2, s[8:9]
	s_waitcnt lgkmcnt(0)
	v_lshl_add_u64 v[8:9], v[0:1], 2, v[8:9]
	v_lshrrev_b32_e32 v0, 8, v4
	v_and_b32_e32 v0, 0xffc, v0
	v_or_b32_e32 v7, 1, v6
	v_lshl_add_u64 v[8:9], v[8:9], 0, v[0:1]
	v_bfe_u32 v0, v5, 16, 5
	global_store_dword v[8:9], v7, off sc1
	v_or_b32_e32 v8, 2, v6
	v_add_u32_e32 v6, 0xffff, v0
	v_mul_u32_u24_e32 v6, v6, v0
	v_lshrrev_b16_e32 v7, 15, v6
	v_add_u16_e32 v6, v6, v7
	v_mul_u32_u24_e32 v5, 31, v0
	v_ashrrev_i16_e32 v6, 1, v6
	v_lshl_add_u32 v0, v0, 2, s10
	v_sub_u16_e32 v6, 0, v6
	ds_read_b32 v0, v0
	v_bfe_i32 v6, v6, 0, 16
	v_add_lshl_u32 v6, v5, v6, 8
	v_ashrrev_i32_e32 v7, 31, v6
	v_lshl_add_u64 v[6:7], v[6:7], 2, s[8:9]
	s_waitcnt lgkmcnt(0)
	v_lshl_add_u64 v[6:7], v[0:1], 2, v[6:7]
	v_lshrrev_b32_e32 v0, 18, v4
	v_and_b32_e32 v0, 0xffc, v0
	v_lshl_add_u64 v[4:5], v[6:7], 0, v[0:1]
	global_store_dword v[4:5], v8, off sc1
.LBB0_616:
	v_add_u32_e32 v0, 0x24400, v2
	ds_read_b32 v5, v0
	v_add_u32_e32 v0, 0x24c00, v2
	ds_read_b32 v4, v0
	s_add_i32 s10, 0, 0x1e300
	v_add_u32_e32 v6, 0x800, v3
	s_waitcnt lgkmcnt(1)
	v_and_b32_e32 v0, 31, v5
	v_add_u32_e32 v8, 0xffff, v0
	v_mul_u32_u24_e32 v8, v8, v0
	v_lshrrev_b16_e32 v9, 15, v8
	v_add_u16_e32 v8, v8, v9
	v_mul_u32_u24_e32 v7, 31, v0
	v_ashrrev_i16_e32 v8, 1, v8
	v_lshl_add_u32 v0, v0, 2, s10
	v_sub_u16_e32 v8, 0, v8
	ds_read_b32 v0, v0
	v_bfe_i32 v8, v8, 0, 16
	v_add_lshl_u32 v8, v7, v8, 8
	v_ashrrev_i32_e32 v9, 31, v8
	s_waitcnt lgkmcnt(1)
	v_and_b32_e32 v7, 0x3ff, v4
	v_lshl_add_u64 v[8:9], v[8:9], 2, s[8:9]
	s_waitcnt lgkmcnt(0)
	v_lshl_add_u64 v[8:9], v[0:1], 2, v[8:9]
	v_lshlrev_b32_e32 v0, 2, v7
	v_lshl_add_u64 v[8:9], v[8:9], 0, v[0:1]
	v_bfe_u32 v0, v5, 8, 5
	global_store_dword v[8:9], v6, off sc1
	v_add_u32_e32 v9, 0xffff, v0
	v_mul_u32_u24_e32 v9, v9, v0
	v_lshrrev_b16_e32 v10, 15, v9
	v_add_u16_e32 v9, v9, v10
	v_mul_u32_u24_e32 v8, 31, v0
	v_ashrrev_i16_e32 v9, 1, v9
	v_lshl_add_u32 v0, v0, 2, s10
	v_sub_u16_e32 v9, 0, v9
	ds_read_b32 v0, v0
	v_bfe_i32 v9, v9, 0, 16
	v_add_lshl_u32 v8, v8, v9, 8
	v_ashrrev_i32_e32 v9, 31, v8
	v_lshl_add_u64 v[8:9], v[8:9], 2, s[8:9]
	s_waitcnt lgkmcnt(0)
	v_lshl_add_u64 v[8:9], v[0:1], 2, v[8:9]
	v_lshrrev_b32_e32 v0, 8, v4
	v_and_b32_e32 v0, 0xffc, v0
	v_add_u32_e32 v7, 0x801, v3
	v_lshl_add_u64 v[0:1], v[8:9], 0, v[0:1]
	s_and_b64 vcc, exec, s[4:5]
	global_store_dword v[0:1], v7, off sc1
	s_cbranch_vccnz .LBB0_618
	v_bfe_u32 v0, v5, 16, 5
	v_or_b32_e32 v5, 2, v6
	v_add_u32_e32 v6, 0xffff, v0
	v_mul_u32_u24_e32 v6, v6, v0
	v_lshrrev_b16_e32 v7, 15, v6
	v_mul_u32_u24_e32 v1, 31, v0
	v_add_u16_e32 v6, v6, v7
	v_lshl_add_u32 v0, v0, 2, 0
	v_ashrrev_i16_e32 v6, 1, v6
	v_add_u32_e32 v0, 0x1e300, v0
	v_sub_u16_e32 v6, 0, v6
	ds_read_b32 v0, v0
	v_bfe_i32 v6, v6, 0, 16
	v_add_lshl_u32 v6, v1, v6, 8
	v_ashrrev_i32_e32 v7, 31, v6
	v_mov_b32_e32 v1, 0
	v_lshl_add_u64 v[6:7], v[6:7], 2, s[8:9]
	s_waitcnt lgkmcnt(0)
	v_lshl_add_u64 v[6:7], v[0:1], 2, v[6:7]
	v_lshrrev_b32_e32 v0, 18, v4
	v_and_b32_e32 v0, 0xffc, v0
	v_lshl_add_u64 v[0:1], v[6:7], 0, v[0:1]
	global_store_dword v[0:1], v5, off sc1
.LBB0_618:
	v_add_u32_e32 v0, 0x25400, v2
	ds_read_b32 v6, v0
	v_add_u32_e32 v0, 0x25c00, v2
	s_add_i32 s4, 0, 0x1e380
	ds_read_b32 v7, v0
	v_add_u32_e32 v2, 0xc00, v3
	s_waitcnt lgkmcnt(1)
	v_and_b32_e32 v1, 31, v6
	v_add_u32_e32 v4, 0xffff, v1
	v_mul_u32_u24_e32 v4, v4, v1
	v_lshrrev_b16_e32 v5, 15, v4
	v_add_u16_e32 v4, v4, v5
	v_ashrrev_i16_e32 v4, 1, v4
	v_sub_u16_e32 v4, 0, v4
	v_mul_u32_u24_e32 v0, 31, v1
	v_bfe_i32 v4, v4, 0, 16
	v_lshl_add_u32 v1, v1, 2, s4
	v_add_lshl_u32 v0, v0, v4, 8
	ds_read_b32 v4, v1
	v_ashrrev_i32_e32 v1, 31, v0
	v_mov_b32_e32 v5, 0
	s_waitcnt lgkmcnt(1)
	v_and_b32_e32 v8, 0x3ff, v7
	v_lshl_add_u64 v[0:1], v[0:1], 2, s[8:9]
	s_waitcnt lgkmcnt(0)
	v_lshl_add_u64 v[0:1], v[4:5], 2, v[0:1]
	v_lshlrev_b32_e32 v4, 2, v8
	v_lshl_add_u64 v[0:1], v[0:1], 0, v[4:5]
	global_store_dword v[0:1], v2, off sc1
	v_bfe_u32 v0, v6, 8, 5
	v_add_u32_e32 v4, 0xffff, v0
	v_mul_u32_u24_e32 v4, v4, v0
	v_lshrrev_b16_e32 v8, 15, v4
	v_add_u16_e32 v4, v4, v8
	v_mul_u32_u24_e32 v1, 31, v0
	v_ashrrev_i16_e32 v4, 1, v4
	v_lshl_add_u32 v0, v0, 2, s4
	v_sub_u16_e32 v8, 0, v4
	ds_read_b32 v4, v0
	v_bfe_i32 v0, v8, 0, 16
	v_add_lshl_u32 v0, v1, v0, 8
	v_ashrrev_i32_e32 v1, 31, v0
	v_lshl_add_u64 v[0:1], v[0:1], 2, s[8:9]
	s_waitcnt lgkmcnt(0)
	v_lshl_add_u64 v[0:1], v[4:5], 2, v[0:1]
	v_lshrrev_b32_e32 v4, 8, v7
	v_and_b32_e32 v4, 0xffc, v4
	v_add_u32_e32 v2, 0xc01, v3
	v_lshl_add_u64 v[0:1], v[0:1], 0, v[4:5]
	global_store_dword v[0:1], v2, off sc1
	v_bfe_u32 v0, v6, 16, 5
	v_add_u32_e32 v2, 0xc02, v3
	v_add_u32_e32 v3, 0xffff, v0
	v_mul_u32_u24_e32 v3, v3, v0
	v_lshrrev_b16_e32 v4, 15, v3
	v_add_u16_e32 v3, v3, v4
	v_mul_u32_u24_e32 v1, 31, v0
	v_ashrrev_i16_e32 v3, 1, v3
	v_lshl_add_u32 v0, v0, 2, s4
	v_sub_u16_e32 v3, 0, v3
	ds_read_b32 v4, v0
	v_bfe_i32 v0, v3, 0, 16
	v_add_lshl_u32 v0, v1, v0, 8
	v_ashrrev_i32_e32 v1, 31, v0
	v_lshl_add_u64 v[0:1], v[0:1], 2, s[8:9]
	v_lshrrev_b32_e32 v3, 18, v7
	s_waitcnt lgkmcnt(0)
	v_lshl_add_u64 v[0:1], v[4:5], 2, v[0:1]
	v_and_b32_e32 v4, 0xffc, v3
	v_lshl_add_u64 v[0:1], v[0:1], 0, v[4:5]
	global_store_dword v[0:1], v2, off sc1
